# conversion slices split: finish the pending half tile right after each staging-loop barrier, issue the next loads right before the next barrier (loads land during the barrier wait; stagers' counted wa
# baseline (speedup 1.0000x reference)
; __device__ __forceinline__ void convert_mats(Frame& F, int m_lo, int m_hi, int gw, int NGW) {
;     ...
;         while (it < base + cnt) {
;             f32x4 va[2][8], vb[2][8];
;             const int lim = base + cnt, i1 = it + NGW;
;             conv_load(src, mt.K, mt.N, mt.Np, it - base, F.lane, va);
;             if (i1 < lim) conv_load(src, mt.K, mt.N, mt.Np, i1 - base, F.lane, vb);
;             conv_proc(va, gain, mt.K, mt.Kp, mt.Np, mt.ilv, dst, scr, it - base, F.lane);
;             if (i1 < lim) conv_proc(vb, gain, mt.K, mt.Kp, mt.Np, mt.ilv, dst, scr, i1 - base, F.lane);
;             it = (i1 < lim) ? i1 + NGW : i1;
; __device__ __forceinline__ void rwkv_scan_phase(Frame& F, const bf16* RKV, const float* WAG, const bf16* AGB, const float* k_k, const float* k_a, const float* r_k, bf16* Y, float* BS, float* ST2) {
;     ...
;             for (int ci = 0; ci < NCH; ci += 2) {
;                 if (ci >= 1) ST_FLUSH(ci - 1);
;                 if (ci + 2 < NCH) ST_LOAD(RA, ci + 2);
;                 ST_PROC(RB, ci + 1);
;                 __syncthreads();
;                 ST_FLUSH(ci);
;                 if (ci + 3 < NCH) ST_LOAD(RB, ci + 3);
;                 if (ci + 2 < NCH) ST_PROC(RA, ci + 2);
;                 __syncthreads();
.LBB0_1786:
	s_cmp_lt_u32 s80, 5
	s_cbranch_scc1 .Lcsb_end
	s_cmp_eq_u32 s66, 0
	s_cbranch_scc0 .Lcsb_nexttile
	s_mov_b32 s66, 1
	s_branch .Lcsb_find

; #define GAS __attribute__((address_space(1)))
; __device__ __forceinline__ void conv_load(const float* W, int K, int N, int Np, int item, int lane, f32x4 (&v)[2][8]) {
;     const int nblk = Np / 64, kb = item / nblk, nb = item % nblk, k0 = 64 * kb, n0 = 64 * nb;
;     const int kr = lane >> 3, n4 = lane & 7;
; #pragma unroll
;     for (int hf = 0; hf < 2; ++hf)
; #pragma unroll
;         for (int i = 0; i < 8; ++i) { const int k = k0 + 8 * i + kr, n = n0 + 32 * hf + 4 * n4;
;             v[hf][i] = (k < K && n < N) ? __builtin_nontemporal_load((const GAS f32x4*)(W + (size_t)k * N + n)) : (f32x4){0.f, 0.f, 0.f, 0.f}; }
; }
; __device__ __forceinline__ void convert_mats(Frame& F, int m_lo, int m_hi, int gw, int NGW) {
;     ...
;         while (it < base + cnt) {
;             f32x4 va[2][8], vb[2][8];
;             const int lim = base + cnt, i1 = it + NGW;
;             conv_load(src, mt.K, mt.N, mt.Np, it - base, F.lane, va);
;             if (i1 < lim) conv_load(src, mt.K, mt.N, mt.Np, i1 - base, F.lane, vb);
;             conv_proc(va, gain, mt.K, mt.Kp, mt.Np, mt.ilv, dst, scr, it - base, F.lane);
;             if (i1 < lim) conv_proc(vb, gain, mt.K, mt.Kp, mt.Np, mt.ilv, dst, scr, i1 - base, F.lane);
;             it = (i1 < lim) ? i1 + NGW : i1;
;         }
; __device__ __forceinline__ void rwkv_scan_phase(Frame& F, const bf16* RKV, const float* WAG, const bf16* AGB, const float* k_k, const float* k_a, const float* r_k, bf16* Y, float* BS, float* ST2) {
;     ...
;             for (int ci = 0; ci < NCH; ci += 2) {
;                 if (ci >= 1) ST_FLUSH(ci - 1);
;                 if (ci + 2 < NCH) ST_LOAD(RA, ci + 2);
;                 ST_PROC(RB, ci + 1);
;                 __syncthreads();
;                 ST_FLUSH(ci);
;                 if (ci + 3 < NCH) ST_LOAD(RB, ci + 3);
;                 if (ci + 2 < NCH) ST_PROC(RA, ci + 2);
;                 __syncthreads();
.Lcsb_noilv:
	s_lshl_b32 s92, s66, 5
	s_add_u32 s95, s95, s92
	s_mul_i32 s95, s95, s85
	s_lshl_b32 s92, s93, 7
	s_add_u32 s95, s95, s92
	s_add_u32 s78, s78, s95
	s_addc_u32 s79, s79, 0
	s_mov_b32 s81, s85
	s_mov_b32 s69, 1
	v_mbcnt_lo_u32_b32 v243, -1, 0
	v_mbcnt_hi_u32_b32 v243, -1, v243
	v_lshrrev_b32_e32 v241, 3, v243
	v_and_b32_e32 v242, 7, v243
	v_mul_lo_u32 v243, v241, s84
	v_lshl_add_u32 v236, v242, 4, v243
	v_lshlrev_b32_e32 v237, 2, v241
	s_lshl_b32 s92, s84, 3
	global_load_dwordx4 v[188:191], v236, s[74:75] nt
	s_add_u32 s74, s74, s92
	s_addc_u32 s75, s75, 0
	global_load_dwordx4 v[192:195], v236, s[74:75] nt
	s_add_u32 s74, s74, s92
	s_addc_u32 s75, s75, 0
	global_load_dwordx4 v[196:199], v236, s[74:75] nt
	s_add_u32 s74, s74, s92
	s_addc_u32 s75, s75, 0
	global_load_dwordx4 v[200:203], v236, s[74:75] nt
	s_add_u32 s74, s74, s92
	s_addc_u32 s75, s75, 0
	global_load_dwordx4 v[204:207], v236, s[74:75] nt
	s_add_u32 s74, s74, s92
	s_addc_u32 s75, s75, 0
	global_load_dwordx4 v[208:211], v236, s[74:75] nt
	s_add_u32 s74, s74, s92
	s_addc_u32 s75, s75, 0
	global_load_dwordx4 v[212:215], v236, s[74:75] nt
	s_add_u32 s74, s74, s92
	s_addc_u32 s75, s75, 0
	global_load_dwordx4 v[216:219], v236, s[74:75] nt
	s_cmp_eq_u32 s71, 0
	s_cbranch_scc1 .Lcsb_end
	s_cmp_eq_u32 s66, 0
	s_cbranch_scc0 .Lcsb_end
	global_load_dword v220, v237, s[76:77]
	global_load_dword v221, v237, s[76:77] offset:32
	global_load_dword v222, v237, s[76:77] offset:64
	global_load_dword v223, v237, s[76:77] offset:96
	global_load_dword v224, v237, s[76:77] offset:128
	global_load_dword v225, v237, s[76:77] offset:160
	global_load_dword v226, v237, s[76:77] offset:192
	global_load_dword v227, v237, s[76:77] offset:224
.Lcsb_end:
	s_add_i32 s58, s58, 2
	v_lshl_add_u64 v[68:69], v[68:69], 0, s[36:37]
	v_lshl_add_u64 v[70:71], v[70:71], 0, s[38:39]
	v_lshl_add_u64 v[72:73], v[72:73], 0, s[40:41]
	v_lshl_add_u64 v[74:75], v[74:75], 0, s[42:43]
	v_lshl_add_u64 v[76:77], v[76:77], 0, s[36:37]
	s_and_b64 vcc, exec, s[48:49]
	s_waitcnt lgkmcnt(0)
	s_barrier
	s_cbranch_vccnz .LBB0_1812

; #define GAS __attribute__((address_space(1)))
; #define LAS __attribute__((address_space(3)))
; #define LDS_WAIT() asm volatile("s_waitcnt lgkmcnt(0)" ::: "memory")
; __device__ __forceinline__ unsigned pk2(float lo, float hi) { unsigned r; asm("v_cvt_pk_bf16_f32 %0, %1, %2" : "=v"(r) : "v"(lo), "v"(hi)); return r; }
; __device__ __forceinline__ void conv_proc(f32x4 (&v)[2][8], const float* gain, int K, int Kp, int Np, int ilv, bf16* WT, LAS float* scr, int item, int lane) {
;     const int nblk = Np / 64, kb = item / nblk, nb = item % nblk, k0 = 64 * kb, n0 = 64 * nb;
;     const int d0 = ilv ? (((n0 % ilv) >> 7) * 256 + (n0 / ilv) * 128 + ((n0 % ilv) & 127)) : n0;
;     const int kr = lane >> 3, n4 = lane & 7;
;     if (gain) {
; #pragma unroll
;         for (int i = 0; i < 8; ++i) { const int k = k0 + 8 * i + kr; const float g = k < K ? gain[k] : 0.f; v[0][i] *= g; v[1][i] *= g; } }
;     const int c = lane & 7;
; #pragma unroll
;     for (int hf = 0; hf < 2; ++hf) {
; #pragma unroll
;         for (int i = 0; i < 8; ++i) { LAS float* d = scr + (8 * i + kr) * 33 + 4 * n4; d[0] = v[hf][i][0]; d[1] = v[hf][i][1]; d[2] = v[hf][i][2]; d[3] = v[hf][i][3]; }
;         LDS_WAIT(); asm volatile("" ::: "memory");
; #pragma unroll
;         for (int j = 0; j < 4; ++j) { const int nn = (lane >> 3) + 8 * j; const LAS float* sp = scr + (8 * c) * 33 + nn;
;             v4u o; o.x = pk2(sp[0 * 33], sp[1 * 33]); o.y = pk2(sp[2 * 33], sp[3 * 33]); o.z = pk2(sp[4 * 33], sp[5 * 33]); o.w = pk2(sp[6 * 33], sp[7 * 33]);
;             __builtin_nontemporal_store(o, (GAS v4u*)(WT + (size_t)(d0 + 32 * hf + nn) * Kp + k0 + 8 * c)); }
;         LDS_WAIT(); asm volatile("" ::: "memory");
;     }
; }
.Lcsap_nogain:
	ds_write_b32 v238, v188 offset:0
	ds_write_b32 v238, v189 offset:4
	ds_write_b32 v238, v190 offset:8
	ds_write_b32 v238, v191 offset:12
	ds_write_b32 v238, v192 offset:1056
	ds_write_b32 v238, v193 offset:1060
	ds_write_b32 v238, v194 offset:1064
	ds_write_b32 v238, v195 offset:1068
	ds_write_b32 v238, v196 offset:2112
	ds_write_b32 v238, v197 offset:2116
	ds_write_b32 v238, v198 offset:2120
	ds_write_b32 v238, v199 offset:2124
	ds_write_b32 v238, v200 offset:3168
	ds_write_b32 v238, v201 offset:3172
	ds_write_b32 v238, v202 offset:3176
	ds_write_b32 v238, v203 offset:3180
	ds_write_b32 v238, v204 offset:4224
	ds_write_b32 v238, v205 offset:4228
	ds_write_b32 v238, v206 offset:4232
	ds_write_b32 v238, v207 offset:4236
	ds_write_b32 v238, v208 offset:5280
	ds_write_b32 v238, v209 offset:5284
	ds_write_b32 v238, v210 offset:5288
	ds_write_b32 v238, v211 offset:5292
	ds_write_b32 v238, v212 offset:6336
	ds_write_b32 v238, v213 offset:6340
	ds_write_b32 v238, v214 offset:6344
	ds_write_b32 v238, v215 offset:6348
	ds_write_b32 v238, v216 offset:7392
	ds_write_b32 v238, v217 offset:7396
	ds_write_b32 v238, v218 offset:7400
	ds_write_b32 v238, v219 offset:7404
	s_waitcnt lgkmcnt(0)
	ds_read2_b32 v[148:149], v239 offset0:0 offset1:33
	ds_read2_b32 v[150:151], v239 offset0:66 offset1:99
	ds_read2_b32 v[152:153], v239 offset0:132 offset1:165
	ds_read2_b32 v[154:155], v239 offset0:198 offset1:231
	ds_read2_b32 v[156:157], v239 offset0:8 offset1:41
	ds_read2_b32 v[158:159], v239 offset0:74 offset1:107
	ds_read2_b32 v[160:161], v239 offset0:140 offset1:173
	ds_read2_b32 v[162:163], v239 offset0:206 offset1:239
	s_waitcnt lgkmcnt(4)
	v_cvt_pk_bf16_f32 v228, v148, v149
	v_cvt_pk_bf16_f32 v229, v150, v151
	v_cvt_pk_bf16_f32 v230, v152, v153
	v_cvt_pk_bf16_f32 v231, v154, v155
	global_store_dwordx4 v240, v[228:231], s[78:79] nt
	ds_read2_b32 v[148:149], v239 offset0:16 offset1:49
	ds_read2_b32 v[150:151], v239 offset0:82 offset1:115
	ds_read2_b32 v[152:153], v239 offset0:148 offset1:181
	ds_read2_b32 v[154:155], v239 offset0:214 offset1:247
	s_waitcnt lgkmcnt(4)
	v_cvt_pk_bf16_f32 v232, v156, v157
	v_cvt_pk_bf16_f32 v233, v158, v159
	v_cvt_pk_bf16_f32 v234, v160, v161
	v_cvt_pk_bf16_f32 v235, v162, v163
	s_mul_i32 s92, s81, 8
	s_add_u32 s94, s78, s92
	s_addc_u32 s95, s79, 0
	global_store_dwordx4 v240, v[232:235], s[94:95] nt
	ds_read2_b32 v[156:157], v239 offset0:24 offset1:57
	ds_read2_b32 v[158:159], v239 offset0:90 offset1:123
	ds_read2_b32 v[160:161], v239 offset0:156 offset1:189
	ds_read2_b32 v[162:163], v239 offset0:222 offset1:255
	s_waitcnt lgkmcnt(4)
	v_cvt_pk_bf16_f32 v228, v148, v149
	v_cvt_pk_bf16_f32 v229, v150, v151
	v_cvt_pk_bf16_f32 v230, v152, v153
	v_cvt_pk_bf16_f32 v231, v154, v155
	s_mul_i32 s92, s81, 16
	s_add_u32 s94, s78, s92
	s_addc_u32 s95, s79, 0
	global_store_dwordx4 v240, v[228:231], s[94:95] nt
	s_waitcnt lgkmcnt(0)
	v_cvt_pk_bf16_f32 v232, v156, v157
	v_cvt_pk_bf16_f32 v233, v158, v159
	v_cvt_pk_bf16_f32 v234, v160, v161
	v_cvt_pk_bf16_f32 v235, v162, v163
	s_mul_i32 s92, s81, 24
	s_add_u32 s94, s78, s92
	s_addc_u32 s95, s79, 0
	global_store_dwordx4 v240, v[232:235], s[94:95] nt
	s_mov_b32 s69, 0

; __device__ __forceinline__ void rwkv_scan_phase(Frame& F, const bf16* RKV, const float* WAG, const bf16* AGB, const float* k_k, const float* k_a, const float* r_k, bf16* Y, float* BS, float* ST2) {
;     ...
;                 ST_PROC(RB, ci + 1);
.LBB0_1797:
	s_or_b64 exec, exec, s[60:61]
	v_add_f32_e32 v181, v181, v182
	v_rsq_f32_e32 v181, v181
	ds_write_b128 v172, v[28:31] offset:45056
	ds_write_b128 v172, v[24:27] offset:53248
	ds_write_b128 v172, v[32:35] offset:61440
	v_max_f32_e64 v28, -v181, s35
	v_pk_mul_f32 v[30:31], v[142:143], v[28:29] op_sel_hi:[1,0]
	v_pk_mul_f32 v[28:29], v[144:145], v[28:29] op_sel_hi:[1,0]
	ds_write_b128 v178, v[28:31]
	v_pk_mul_f32 v[30:31], v[30:31], v[140:141] neg_lo:[1,0] neg_hi:[1,0]
	v_pk_mul_f32 v[28:29], v[28:29], v[138:139] neg_lo:[1,0] neg_hi:[1,0]
	ds_write_b128 v179, v[28:31]
	s_and_saveexec_b64 s[60:61], s[8:9]
	v_lshlrev_b32_e32 v28, 16, v64
	v_and_b32_e32 v29, 0xffff0000, v64
	v_lshlrev_b32_e32 v30, 16, v65
	v_and_b32_e32 v31, 0xffff0000, v65
	ds_write_b128 v180, v[28:31]
	s_or_b64 exec, exec, s[60:61]
	s_cmp_lt_u32 s80, 5
	s_cbranch_scc1 .Lcsa_end
	s_cmp_eq_u32 s66, 0
	s_cbranch_scc0 .Lcsa_nexttile
	s_mov_b32 s66, 1
	s_branch .Lcsa_find

; #define LAS __attribute__((address_space(3)))
; __device__ __forceinline__ void conv_proc(f32x4 (&v)[2][8], const float* gain, int K, int Kp, int Np, int ilv, bf16* WT, LAS float* scr, int item, int lane) {
;     const int nblk = Np / 64, kb = item / nblk, nb = item % nblk, k0 = 64 * kb, n0 = 64 * nb;
;     const int d0 = ilv ? (((n0 % ilv) >> 7) * 256 + (n0 / ilv) * 128 + ((n0 % ilv) & 127)) : n0;
;     const int kr = lane >> 3, n4 = lane & 7;
;     if (gain) {
; #pragma unroll
;         for (int i = 0; i < 8; ++i) { const int k = k0 + 8 * i + kr; const float g = k < K ? gain[k] : 0.f; v[0][i] *= g; v[1][i] *= g; } }
; __device__ __forceinline__ void rwkv_scan_phase(Frame& F, const bf16* RKV, const float* WAG, const bf16* AGB, const float* k_k, const float* k_a, const float* r_k, bf16* Y, float* BS, float* ST2) {
;     ...
;                 __syncthreads();
.Lcsa_end:
	s_waitcnt lgkmcnt(0)
	s_barrier
	s_cmp_lt_u32 s80, 5
	s_cbranch_scc1 .Lcsbp_adv
	s_cmp_eq_u32 s69, 0
	s_cbranch_scc1 .Lcsbp_adv
	v_mbcnt_lo_u32_b32 v243, -1, 0
	v_mbcnt_hi_u32_b32 v243, -1, v243
	s_sub_u32 s92, s80, 5
	s_mul_i32 s92, s92, 0x2100
	s_add_u32 s92, s92, 0x19200
	v_lshrrev_b32_e32 v241, 3, v243
	v_and_b32_e32 v242, 7, v243
	v_mul_u32_u24_e32 v243, 132, v241
	v_lshl_add_u32 v243, v242, 4, v243
	v_add_u32_e32 v238, s92, v243
	v_mul_u32_u24_e32 v243, 0x420, v242
	v_lshl_add_u32 v243, v241, 2, v243
	v_add_u32_e32 v239, s92, v243
	v_mul_lo_u32 v243, v241, s81
	v_lshl_add_u32 v240, v242, 4, v243
	s_waitcnt vmcnt(0)
	s_cmp_eq_u32 s71, 0
	s_cbranch_scc1 .Lcsbp_nogain
	v_pk_mul_f32 v[188:189], v[188:189], v[220:221] op_sel_hi:[1,0]
	v_pk_mul_f32 v[190:191], v[190:191], v[220:221] op_sel_hi:[1,0]
	v_pk_mul_f32 v[192:193], v[192:193], v[220:221] op_sel:[0,1] op_sel_hi:[1,1]
	v_pk_mul_f32 v[194:195], v[194:195], v[220:221] op_sel:[0,1] op_sel_hi:[1,1]
	v_pk_mul_f32 v[196:197], v[196:197], v[222:223] op_sel_hi:[1,0]
	v_pk_mul_f32 v[198:199], v[198:199], v[222:223] op_sel_hi:[1,0]
	v_pk_mul_f32 v[200:201], v[200:201], v[222:223] op_sel:[0,1] op_sel_hi:[1,1]
	v_pk_mul_f32 v[202:203], v[202:203], v[222:223] op_sel:[0,1] op_sel_hi:[1,1]
	v_pk_mul_f32 v[204:205], v[204:205], v[224:225] op_sel_hi:[1,0]
	v_pk_mul_f32 v[206:207], v[206:207], v[224:225] op_sel_hi:[1,0]
	v_pk_mul_f32 v[208:209], v[208:209], v[224:225] op_sel:[0,1] op_sel_hi:[1,1]
	v_pk_mul_f32 v[210:211], v[210:211], v[224:225] op_sel:[0,1] op_sel_hi:[1,1]
	v_pk_mul_f32 v[212:213], v[212:213], v[226:227] op_sel_hi:[1,0]
	v_pk_mul_f32 v[214:215], v[214:215], v[226:227] op_sel_hi:[1,0]
	v_pk_mul_f32 v[216:217], v[216:217], v[226:227] op_sel:[0,1] op_sel_hi:[1,1]
	v_pk_mul_f32 v[218:219], v[218:219], v[226:227] op_sel:[0,1] op_sel_hi:[1,1]
